# v75 + all 160 per-MFMA-block s_setprio flips deleted from the five GEMM K-loops (no static raise)
# speedup vs baseline: 1.0108x; 1.0073x over previous
; #define PG8_STAGE(bufoff, gbase, voff) do { _Pragma("unroll") for (int _i = 0; _i < 2; ++_i) \
;         __builtin_amdgcn_global_load_lds((const unsigned*)((const char*)(gbase) + (voff)[_i]), (PG8_LAS unsigned*)(lds + (bufoff) + ldsw + _i * 8192), 16, 0, 0); } while (0)
; #define PG8_LDA(dst, b, h) do { _Pragma("unroll") for (int m = 0; m < 4; ++m) _Pragma("unroll") for (int k = 0; k < 2; ++k) dst[m][k] = *(const PG8_LAS bf16x8*)(lds + PG8_SA(b, h) + aoff + m * 2048 + k * 1024); } while (0)
; #define PG8_LDB(dst, b, h) do { _Pragma("unroll") for (int n = 0; n < 2; ++n) _Pragma("unroll") for (int k = 0; k < 2; ++k) dst[n][k] = *(const PG8_LAS bf16x8*)(lds + PG8_SB(b, h) + boff + n * 2048 + k * 1024); } while (0)
; #define PG8_MMA(ai, bj, At, Bt) do { __builtin_amdgcn_s_setprio(1); _Pragma("unroll") for (int m = 0; m < 4; ++m) _Pragma("unroll") for (int n = 0; n < 2; ++n) _Pragma("unroll") for (int k = 0; k < 2; ++k) \
;         acc[ai][bj][m][n] = mma16<Epi::I8>(Bt[n][k], At[m][k], acc[ai][bj][m][n]); __builtin_amdgcn_s_setprio(0); } while (0)
; #define PG8_WAIT_V(n) asm volatile("s_waitcnt vmcnt(" #n ")" ::: "memory")
; #define PG8_WAIT_L(n) asm volatile("s_waitcnt lgkmcnt(" #n ")" ::: "memory")
; #define PG8_BAR __builtin_amdgcn_s_barrier()
; template <class Epi, class Sched, bool ALIGN_EPI = false, bool SP2 = false>
; __device__ __forceinline__ void gemm_phase(PG8_LAS unsigned char* lds, const Gemm g, const Sched& S, const Epi& E) {
;     ...
;             const bool last = (t == nt - 2);
;             const char* a1 = cA + (size_t)(t + 1) * kstep;
;             const char* a2 = last ? nA : cA + (size_t)(t + 2) * kstep; const char* b2 = last ? nB : cB + (size_t)(t + 2) * kstep;
;             const char* a3 = a2 + kstep; const char* b3 = b2 + kstep;
;             if (last && has_next) S.a_ready(nxt);
;             if constexpr (SP2) {
;             PG8_LDB(B0, 0, 0); PG8_LDB(B1, 0, 1); PG8_SCHED; PG8_LDA(At, 0, 0); PG8_STAGE(PG8_SA(1, 1), a1 + hstep, voffA);
;             PG8_WAIT_V(8); PG8_WAIT_L(0); PG8_BAR; PG8_MMA(0, 0, At, B0); PG8_MMA(0, 1, At, B1); PG8_BAR; PG8_SCHED;
;             PG8_LDA(At, 0, 1); PG8_STAGE(PG8_SB(0, 0), b2, voffB); PG8_STAGE(PG8_SB(0, 1), b2 + hstep, voffB); PG8_STAGE(PG8_SA(0, 0), a2, voffA);
;             PG8_WAIT_V(8); PG8_WAIT_L(0); PG8_BAR; PG8_MMA(1, 0, At, B0); PG8_MMA(1, 1, At, B1); PG8_BAR; PG8_SCHED;
.Lpeel175:
	s_add_i32 vcc_lo, s8, 2
	s_add_u32 s4, s6, s98
	s_addc_u32 s5, s7, 0
	s_add_i32 vcc_hi, 0, 0x10000
	s_cmp_eq_u32 s13, s8
	s_cselect_b32 s9, s1, s5
	s_cselect_b32 s8, s0, s4
	s_cselect_b32 s5, s97, s85
	s_cselect_b32 s4, s96, s67
	s_add_i32 s84, 0, 0x14000
	v_add_u32_e32 v122, vcc_hi, v248
	v_add_u32_e32 v154, s84, v248
	ds_read_b128 v[98:101], v122
	ds_read_b128 v[102:105], v122 offset:1024
	ds_read_b128 v[114:117], v122 offset:2048
	ds_read_b128 v[122:125], v122 offset:3072
	ds_read_b128 v[130:133], v154
	ds_read_b128 v[138:141], v154 offset:1024
	ds_read_b128 v[146:149], v154 offset:2048
	ds_read_b128 v[154:157], v154 offset:3072
	v_lshl_add_u64 v[206:207], s[6:7], 0, v[200:201]
	s_add_i32 m0, s81, 0xc000
	ds_read_b128 v[162:165], v249
	ds_read_b128 v[166:169], v249 offset:1024
	ds_read_b128 v[170:173], v249 offset:2048
	ds_read_b128 v[174:177], v249 offset:3072
	ds_read_b128 v[178:181], v249 offset:4096
	ds_read_b128 v[182:185], v249 offset:5120
	ds_read_b128 v[186:189], v249 offset:6144
	ds_read_b128 v[190:193], v249 offset:7168
	global_load_lds_dwordx4 v[206:207], off
	v_lshl_add_u64 v[206:207], s[6:7], 0, v[210:211]
	s_add_i32 m0, s81, 0xe000
	s_nop 0
	global_load_lds_dwordx4 v[206:207], off
	s_waitcnt vmcnt(8)
	s_waitcnt lgkmcnt(0)
	s_barrier
	s_waitcnt lgkmcnt(0)
	v_mfma_f32_16x16x32_bf16 v[158:161], v[98:101], v[162:165], 0
	v_mfma_f32_16x16x32_bf16 v[150:153], v[114:117], v[162:165], 0
	v_mfma_f32_16x16x32_bf16 v[118:121], v[114:117], v[170:173], 0
	v_mfma_f32_16x16x32_bf16 v[126:129], v[98:101], v[170:173], 0
	v_mfma_f32_16x16x32_bf16 v[94:97], v[98:101], v[178:181], 0
	v_mfma_f32_16x16x32_bf16 v[90:93], v[114:117], v[178:181], 0
	v_mfma_f32_16x16x32_bf16 v[74:77], v[114:117], v[186:189], 0
	v_mfma_f32_16x16x32_bf16 v[78:81], v[98:101], v[186:189], 0
	v_mfma_f32_16x16x32_bf16 v[158:161], v[102:105], v[166:169], v[158:161]
	v_mfma_f32_16x16x32_bf16 v[150:153], v[122:125], v[166:169], v[150:153]
	v_mfma_f32_16x16x32_bf16 v[118:121], v[122:125], v[174:177], v[118:121]
	v_mfma_f32_16x16x32_bf16 v[126:129], v[102:105], v[174:177], v[126:129]
	v_mfma_f32_16x16x32_bf16 v[94:97], v[102:105], v[182:185], v[94:97]
	v_mfma_f32_16x16x32_bf16 v[90:93], v[122:125], v[182:185], v[90:93]
	v_mfma_f32_16x16x32_bf16 v[74:77], v[122:125], v[190:193], v[74:77]
	v_mfma_f32_16x16x32_bf16 v[78:81], v[102:105], v[190:193], v[78:81]
	v_mfma_f32_16x16x32_bf16 v[142:145], v[130:133], v[162:165], 0
	v_mfma_f32_16x16x32_bf16 v[134:137], v[146:149], v[162:165], 0
	v_mfma_f32_16x16x32_bf16 v[106:109], v[146:149], v[170:173], 0
	v_mfma_f32_16x16x32_bf16 v[110:113], v[130:133], v[170:173], 0
	v_mfma_f32_16x16x32_bf16 v[86:89], v[130:133], v[178:181], 0
	v_mfma_f32_16x16x32_bf16 v[82:85], v[146:149], v[178:181], 0
	v_mfma_f32_16x16x32_bf16 v[66:69], v[146:149], v[186:189], 0
	v_mfma_f32_16x16x32_bf16 v[70:73], v[130:133], v[186:189], 0
	v_mfma_f32_16x16x32_bf16 v[142:145], v[138:141], v[166:169], v[142:145]
	v_mfma_f32_16x16x32_bf16 v[134:137], v[154:157], v[166:169], v[134:137]
	v_mfma_f32_16x16x32_bf16 v[106:109], v[154:157], v[174:177], v[106:109]
	v_mfma_f32_16x16x32_bf16 v[110:113], v[138:141], v[174:177], v[110:113]
	v_mfma_f32_16x16x32_bf16 v[86:89], v[138:141], v[182:185], v[86:89]
	v_mfma_f32_16x16x32_bf16 v[82:85], v[154:157], v[182:185], v[82:85]
	v_mfma_f32_16x16x32_bf16 v[66:69], v[154:157], v[190:193], v[66:69]
	v_mfma_f32_16x16x32_bf16 v[70:73], v[138:141], v[190:193], v[70:73]
	s_barrier
	s_add_i32 vcc_hi, vcc_hi, s80
	v_lshl_add_u64 v[206:207], s[4:5], 0, v[0:1]
	s_mov_b32 m0, vcc_hi
	ds_read_b128 v[162:165], v249 offset:16384
	ds_read_b128 v[166:169], v249 offset:17408
	ds_read_b128 v[170:173], v249 offset:18432
	ds_read_b128 v[174:177], v249 offset:19456
	ds_read_b128 v[178:181], v249 offset:20480
	ds_read_b128 v[182:185], v249 offset:21504
	ds_read_b128 v[186:189], v249 offset:22528
	ds_read_b128 v[190:193], v249 offset:23552
	global_load_lds_dwordx4 v[206:207], off
	s_add_i32 m0, vcc_hi, 0x2000
	v_lshl_add_u64 v[212:213], s[4:5], 0, v[198:199]
	s_add_u32 s4, s4, s100
	s_addc_u32 s5, s5, 0
	s_add_i32 s84, s84, s80
	global_load_lds_dwordx4 v[212:213], off
	v_lshl_add_u64 v[214:215], s[4:5], 0, v[0:1]
	s_mov_b32 m0, s84
	v_lshl_add_u64 v[216:217], s[4:5], 0, v[198:199]
	global_load_lds_dwordx4 v[214:215], off
	s_add_i32 m0, s84, 0x2000
	v_lshl_add_u64 v[218:219], s[8:9], 0, v[194:195]
	global_load_lds_dwordx4 v[216:217], off
	s_mov_b32 m0, s81
	v_lshl_add_u64 v[220:221], s[8:9], 0, v[196:197]
	global_load_lds_dwordx4 v[218:219], off
	s_mov_b32 m0, s70
	s_nop 0
	global_load_lds_dwordx4 v[220:221], off
	s_waitcnt vmcnt(8)
	s_waitcnt lgkmcnt(0)
	s_barrier
; #define PG8_STAGE(bufoff, gbase, voff) do { _Pragma("unroll") for (int _i = 0; _i < 2; ++_i) \
;         __builtin_amdgcn_global_load_lds((const unsigned*)((const char*)(gbase) + (voff)[_i]), (PG8_LAS unsigned*)(lds + (bufoff) + ldsw + _i * 8192), 16, 0, 0); } while (0)
; #define PG8_LDA(dst, b, h) do { _Pragma("unroll") for (int m = 0; m < 4; ++m) _Pragma("unroll") for (int k = 0; k < 2; ++k) dst[m][k] = *(const PG8_LAS bf16x8*)(lds + PG8_SA(b, h) + aoff + m * 2048 + k * 1024); } while (0)
; #define PG8_LDB(dst, b, h) do { _Pragma("unroll") for (int n = 0; n < 2; ++n) _Pragma("unroll") for (int k = 0; k < 2; ++k) dst[n][k] = *(const PG8_LAS bf16x8*)(lds + PG8_SB(b, h) + boff + n * 2048 + k * 1024); } while (0)
; #define PG8_MMA(ai, bj, At, Bt) do { __builtin_amdgcn_s_setprio(1); _Pragma("unroll") for (int m = 0; m < 4; ++m) _Pragma("unroll") for (int n = 0; n < 2; ++n) _Pragma("unroll") for (int k = 0; k < 2; ++k) \
;         acc[ai][bj][m][n] = mma16<Epi::I8>(Bt[n][k], At[m][k], acc[ai][bj][m][n]); __builtin_amdgcn_s_setprio(0); } while (0)
; #define PG8_WAIT_V(n) asm volatile("s_waitcnt vmcnt(" #n ")" ::: "memory")
; #define PG8_WAIT_L(n) asm volatile("s_waitcnt lgkmcnt(" #n ")" ::: "memory")
; #define PG8_BAR __builtin_amdgcn_s_barrier()
; #define PG8_SCHED __builtin_amdgcn_sched_barrier(0)
; template <class Epi, class Sched, bool ALIGN_EPI = false, bool SP2 = false>
; __device__ __forceinline__ void gemm_phase(PG8_LAS unsigned char* lds, const Gemm g, const Sched& S, const Epi& E) {
;     ...
;             PG8_WAIT_V(8); PG8_WAIT_L(0); PG8_BAR; PG8_MMA(1, 0, At, B0); PG8_MMA(1, 1, At, B1); PG8_BAR; PG8_SCHED;
;             PG8_LDB(B0, 1, 0); PG8_LDB(B1, 1, 1); PG8_SCHED; PG8_LDA(At, 1, 0); PG8_STAGE(PG8_SA(0, 1), a2 + hstep, voffA);
;             PG8_WAIT_V(8); PG8_WAIT_L(0); PG8_BAR; PG8_MMA(0, 0, At, B0); PG8_MMA(0, 1, At, B1); PG8_BAR; PG8_SCHED;
	s_waitcnt lgkmcnt(0)
	v_mfma_f32_16x16x32_bf16 v[62:65], v[98:101], v[162:165], 0
	v_mfma_f32_16x16x32_bf16 v[58:61], v[114:117], v[162:165], 0
	v_mfma_f32_16x16x32_bf16 v[42:45], v[114:117], v[170:173], 0
	v_mfma_f32_16x16x32_bf16 v[46:49], v[98:101], v[170:173], 0
	v_mfma_f32_16x16x32_bf16 v[30:33], v[98:101], v[178:181], 0
	v_mfma_f32_16x16x32_bf16 v[26:29], v[114:117], v[178:181], 0
	v_mfma_f32_16x16x32_bf16 v[10:13], v[114:117], v[186:189], 0
	v_mfma_f32_16x16x32_bf16 v[14:17], v[98:101], v[186:189], 0
	v_mfma_f32_16x16x32_bf16 v[62:65], v[102:105], v[166:169], v[62:65]
	v_mfma_f32_16x16x32_bf16 v[58:61], v[122:125], v[166:169], v[58:61]
	v_mfma_f32_16x16x32_bf16 v[42:45], v[122:125], v[174:177], v[42:45]
	v_mfma_f32_16x16x32_bf16 v[46:49], v[102:105], v[174:177], v[46:49]
	v_mfma_f32_16x16x32_bf16 v[30:33], v[102:105], v[182:185], v[30:33]
	v_mfma_f32_16x16x32_bf16 v[26:29], v[122:125], v[182:185], v[26:29]
	v_mfma_f32_16x16x32_bf16 v[10:13], v[122:125], v[190:193], v[10:13]
	v_mfma_f32_16x16x32_bf16 v[14:17], v[102:105], v[190:193], v[14:17]
	v_mfma_f32_16x16x32_bf16 v[54:57], v[130:133], v[162:165], 0
	v_mfma_f32_16x16x32_bf16 v[50:53], v[146:149], v[162:165], 0
	v_mfma_f32_16x16x32_bf16 v[34:37], v[146:149], v[170:173], 0
	v_mfma_f32_16x16x32_bf16 v[38:41], v[130:133], v[170:173], 0
	v_mfma_f32_16x16x32_bf16 v[22:25], v[130:133], v[178:181], 0
	v_mfma_f32_16x16x32_bf16 v[18:21], v[146:149], v[178:181], 0
	v_mfma_f32_16x16x32_bf16 v[2:5], v[146:149], v[186:189], 0
	v_mfma_f32_16x16x32_bf16 v[6:9], v[130:133], v[186:189], 0
	v_mfma_f32_16x16x32_bf16 v[54:57], v[138:141], v[166:169], v[54:57]
	v_mfma_f32_16x16x32_bf16 v[50:53], v[154:157], v[166:169], v[50:53]
	v_mfma_f32_16x16x32_bf16 v[34:37], v[154:157], v[174:177], v[34:37]
	v_mfma_f32_16x16x32_bf16 v[38:41], v[138:141], v[174:177], v[38:41]
	v_mfma_f32_16x16x32_bf16 v[22:25], v[138:141], v[182:185], v[22:25]
	v_mfma_f32_16x16x32_bf16 v[18:21], v[154:157], v[182:185], v[18:21]
	v_mfma_f32_16x16x32_bf16 v[2:5], v[154:157], v[190:193], v[2:5]
	v_mfma_f32_16x16x32_bf16 v[6:9], v[138:141], v[190:193], v[6:9]
	s_barrier
	s_add_i32 s84, 0, 0x18000
	s_add_i32 vcc_hi, 0, 0x1c000
	v_add_u32_e32 v122, s84, v248
	v_add_u32_e32 v154, vcc_hi, v248
	ds_read_b128 v[98:101], v122
	ds_read_b128 v[102:105], v122 offset:1024
	ds_read_b128 v[114:117], v122 offset:2048
	ds_read_b128 v[122:125], v122 offset:3072
	ds_read_b128 v[130:133], v154
	ds_read_b128 v[138:141], v154 offset:1024
	ds_read_b128 v[146:149], v154 offset:2048
	ds_read_b128 v[154:157], v154 offset:3072
	s_add_u32 s4, s8, s100
	s_addc_u32 s5, s9, 0
	s_mov_b32 m0, s71
	v_lshl_add_u64 v[222:223], s[4:5], 0, v[194:195]
	ds_read_b128 v[162:165], v249 offset:32768
	ds_read_b128 v[166:169], v249 offset:33792
	ds_read_b128 v[170:173], v249 offset:34816
	ds_read_b128 v[174:177], v249 offset:35840
	ds_read_b128 v[178:181], v249 offset:36864
	ds_read_b128 v[182:185], v249 offset:37888
	ds_read_b128 v[186:189], v249 offset:38912
	ds_read_b128 v[190:193], v249 offset:39936
	global_load_lds_dwordx4 v[222:223], off
	v_lshl_add_u64 v[222:223], s[4:5], 0, v[196:197]
	s_mov_b32 m0, s12
	s_nop 0
	global_load_lds_dwordx4 v[222:223], off
	s_waitcnt vmcnt(8)
	s_waitcnt lgkmcnt(0)
	s_barrier
	s_waitcnt lgkmcnt(0)
	v_mfma_f32_16x16x32_bf16 v[158:161], v[98:101], v[162:165], v[158:161]
	v_mfma_f32_16x16x32_bf16 v[150:153], v[114:117], v[162:165], v[150:153]
	v_mfma_f32_16x16x32_bf16 v[118:121], v[114:117], v[170:173], v[118:121]
	v_mfma_f32_16x16x32_bf16 v[126:129], v[98:101], v[170:173], v[126:129]
	v_mfma_f32_16x16x32_bf16 v[94:97], v[98:101], v[178:181], v[94:97]
	v_mfma_f32_16x16x32_bf16 v[90:93], v[114:117], v[178:181], v[90:93]
	v_mfma_f32_16x16x32_bf16 v[74:77], v[114:117], v[186:189], v[74:77]
	v_mfma_f32_16x16x32_bf16 v[78:81], v[98:101], v[186:189], v[78:81]
	v_mfma_f32_16x16x32_bf16 v[158:161], v[102:105], v[166:169], v[158:161]
	v_mfma_f32_16x16x32_bf16 v[150:153], v[122:125], v[166:169], v[150:153]
	v_mfma_f32_16x16x32_bf16 v[118:121], v[122:125], v[174:177], v[118:121]
	v_mfma_f32_16x16x32_bf16 v[126:129], v[102:105], v[174:177], v[126:129]
	v_mfma_f32_16x16x32_bf16 v[94:97], v[102:105], v[182:185], v[94:97]
	v_mfma_f32_16x16x32_bf16 v[90:93], v[122:125], v[182:185], v[90:93]
	v_mfma_f32_16x16x32_bf16 v[74:77], v[122:125], v[190:193], v[74:77]
	v_mfma_f32_16x16x32_bf16 v[78:81], v[102:105], v[190:193], v[78:81]
	v_mfma_f32_16x16x32_bf16 v[142:145], v[130:133], v[162:165], v[142:145]
	v_mfma_f32_16x16x32_bf16 v[134:137], v[146:149], v[162:165], v[134:137]
	v_mfma_f32_16x16x32_bf16 v[106:109], v[146:149], v[170:173], v[106:109]
	v_mfma_f32_16x16x32_bf16 v[110:113], v[130:133], v[170:173], v[110:113]
	v_mfma_f32_16x16x32_bf16 v[86:89], v[130:133], v[178:181], v[86:89]
	v_mfma_f32_16x16x32_bf16 v[82:85], v[146:149], v[178:181], v[82:85]
	v_mfma_f32_16x16x32_bf16 v[66:69], v[146:149], v[186:189], v[66:69]
	v_mfma_f32_16x16x32_bf16 v[70:73], v[130:133], v[186:189], v[70:73]
	v_mfma_f32_16x16x32_bf16 v[142:145], v[138:141], v[166:169], v[142:145]
	v_mfma_f32_16x16x32_bf16 v[134:137], v[154:157], v[166:169], v[134:137]
	v_mfma_f32_16x16x32_bf16 v[106:109], v[154:157], v[174:177], v[106:109]
	v_mfma_f32_16x16x32_bf16 v[110:113], v[138:141], v[174:177], v[110:113]
	v_mfma_f32_16x16x32_bf16 v[86:89], v[138:141], v[182:185], v[86:89]
	v_mfma_f32_16x16x32_bf16 v[82:85], v[154:157], v[182:185], v[82:85]
	v_mfma_f32_16x16x32_bf16 v[66:69], v[154:157], v[190:193], v[66:69]
	v_mfma_f32_16x16x32_bf16 v[70:73], v[138:141], v[190:193], v[70:73]
	s_barrier
; #define PG8_STAGE(bufoff, gbase, voff) do { _Pragma("unroll") for (int _i = 0; _i < 2; ++_i) \
;         __builtin_amdgcn_global_load_lds((const unsigned*)((const char*)(gbase) + (voff)[_i]), (PG8_LAS unsigned*)(lds + (bufoff) + ldsw + _i * 8192), 16, 0, 0); } while (0)
; #define PG8_LDA(dst, b, h) do { _Pragma("unroll") for (int m = 0; m < 4; ++m) _Pragma("unroll") for (int k = 0; k < 2; ++k) dst[m][k] = *(const PG8_LAS bf16x8*)(lds + PG8_SA(b, h) + aoff + m * 2048 + k * 1024); } while (0)
; #define PG8_LDB(dst, b, h) do { _Pragma("unroll") for (int n = 0; n < 2; ++n) _Pragma("unroll") for (int k = 0; k < 2; ++k) dst[n][k] = *(const PG8_LAS bf16x8*)(lds + PG8_SB(b, h) + boff + n * 2048 + k * 1024); } while (0)
; #define PG8_MMA(ai, bj, At, Bt) do { __builtin_amdgcn_s_setprio(1); _Pragma("unroll") for (int m = 0; m < 4; ++m) _Pragma("unroll") for (int n = 0; n < 2; ++n) _Pragma("unroll") for (int k = 0; k < 2; ++k) \
;         acc[ai][bj][m][n] = mma16<Epi::I8>(Bt[n][k], At[m][k], acc[ai][bj][m][n]); __builtin_amdgcn_s_setprio(0); } while (0)
; #define PG8_WAIT_V(n) asm volatile("s_waitcnt vmcnt(" #n ")" ::: "memory")
; #define PG8_WAIT_L(n) asm volatile("s_waitcnt lgkmcnt(" #n ")" ::: "memory")
; #define PG8_BAR __builtin_amdgcn_s_barrier()
; template <class Epi, class Sched, bool ALIGN_EPI = false, bool SP2 = false>
; __device__ __forceinline__ void gemm_phase(PG8_LAS unsigned char* lds, const Gemm g, const Sched& S, const Epi& E) {
;     ...
;             const bool last = (t == nt - 2);
;             const char* a1 = cA + (size_t)(t + 1) * kstep;
;             const char* a2 = last ? nA : cA + (size_t)(t + 2) * kstep; const char* b2 = last ? nB : cB + (size_t)(t + 2) * kstep;
;             const char* a3 = a2 + kstep; const char* b3 = b2 + kstep;
;             if (last && has_next) S.a_ready(nxt);
;             if constexpr (SP2) {
;             PG8_LDB(B0, 0, 0); PG8_LDB(B1, 0, 1); PG8_SCHED; PG8_LDA(At, 0, 0); PG8_STAGE(PG8_SA(1, 1), a1 + hstep, voffA);
;             PG8_WAIT_V(8); PG8_WAIT_L(0); PG8_BAR; PG8_MMA(0, 0, At, B0); PG8_MMA(0, 1, At, B1); PG8_BAR; PG8_SCHED;
;     ...
;             PG8_LDA(At, 1, 1); PG8_STAGE(PG8_SB(1, 0), b3, voffB); PG8_STAGE(PG8_SB(1, 1), b3 + hstep, voffB); PG8_STAGE(PG8_SA(1, 0), a3, voffA);
;             PG8_WAIT_V(8); PG8_WAIT_L(0); PG8_BAR; PG8_MMA(1, 0, At, B0); PG8_MMA(1, 1, At, B1); PG8_BAR; PG8_SCHED;
	s_add_i32 s4, s84, s80
	v_lshl_add_u64 v[206:207], v[206:207], 0, s[98:99]
	s_mov_b32 m0, s4
	ds_read_b128 v[162:165], v249 offset:49152
	ds_read_b128 v[166:169], v249 offset:50176
	ds_read_b128 v[170:173], v249 offset:51200
	ds_read_b128 v[174:177], v249 offset:52224
	ds_read_b128 v[178:181], v249 offset:53248
	ds_read_b128 v[182:185], v249 offset:54272
	ds_read_b128 v[186:189], v249 offset:55296
	ds_read_b128 v[190:193], v249 offset:56320
	global_load_lds_dwordx4 v[206:207], off
	v_lshl_add_u64 v[206:207], v[212:213], 0, s[98:99]
	s_add_i32 m0, s4, 0x2000
	s_add_i32 s4, vcc_hi, s80
	global_load_lds_dwordx4 v[206:207], off
	v_lshl_add_u64 v[206:207], v[214:215], 0, s[98:99]
	s_mov_b32 m0, s4
	s_nop 0
	global_load_lds_dwordx4 v[206:207], off
	v_lshl_add_u64 v[206:207], v[216:217], 0, s[98:99]
	s_add_i32 m0, s4, 0x2000
	s_nop 0
	global_load_lds_dwordx4 v[206:207], off
	v_lshl_add_u64 v[206:207], v[218:219], 0, s[98:99]
	s_mov_b32 m0, s10
	s_nop 0
	global_load_lds_dwordx4 v[206:207], off
	v_lshl_add_u64 v[206:207], v[220:221], 0, s[98:99]
	s_mov_b32 m0, s11
	s_nop 0
	global_load_lds_dwordx4 v[206:207], off
	s_waitcnt vmcnt(8)
	s_waitcnt lgkmcnt(0)
	s_barrier
	s_waitcnt lgkmcnt(0)
	v_mfma_f32_16x16x32_bf16 v[62:65], v[98:101], v[162:165], v[62:65]
	v_mfma_f32_16x16x32_bf16 v[58:61], v[114:117], v[162:165], v[58:61]
	v_mfma_f32_16x16x32_bf16 v[42:45], v[114:117], v[170:173], v[42:45]
	v_mfma_f32_16x16x32_bf16 v[46:49], v[98:101], v[170:173], v[46:49]
	v_mfma_f32_16x16x32_bf16 v[30:33], v[98:101], v[178:181], v[30:33]
	v_mfma_f32_16x16x32_bf16 v[26:29], v[114:117], v[178:181], v[26:29]
	v_mfma_f32_16x16x32_bf16 v[10:13], v[114:117], v[186:189], v[10:13]
	v_mfma_f32_16x16x32_bf16 v[14:17], v[98:101], v[186:189], v[14:17]
	v_mfma_f32_16x16x32_bf16 v[62:65], v[102:105], v[166:169], v[62:65]
	v_mfma_f32_16x16x32_bf16 v[58:61], v[122:125], v[166:169], v[58:61]
	v_mfma_f32_16x16x32_bf16 v[42:45], v[122:125], v[174:177], v[42:45]
	v_mfma_f32_16x16x32_bf16 v[46:49], v[102:105], v[174:177], v[46:49]
	v_mfma_f32_16x16x32_bf16 v[30:33], v[102:105], v[182:185], v[30:33]
	v_mfma_f32_16x16x32_bf16 v[26:29], v[122:125], v[182:185], v[26:29]
	v_mfma_f32_16x16x32_bf16 v[10:13], v[122:125], v[190:193], v[10:13]
	v_mfma_f32_16x16x32_bf16 v[14:17], v[102:105], v[190:193], v[14:17]
	v_mfma_f32_16x16x32_bf16 v[54:57], v[130:133], v[162:165], v[54:57]
	v_mfma_f32_16x16x32_bf16 v[50:53], v[146:149], v[162:165], v[50:53]
	v_mfma_f32_16x16x32_bf16 v[34:37], v[146:149], v[170:173], v[34:37]
	v_mfma_f32_16x16x32_bf16 v[38:41], v[130:133], v[170:173], v[38:41]
	v_mfma_f32_16x16x32_bf16 v[22:25], v[130:133], v[178:181], v[22:25]
	v_mfma_f32_16x16x32_bf16 v[18:21], v[146:149], v[178:181], v[18:21]
	v_mfma_f32_16x16x32_bf16 v[2:5], v[146:149], v[186:189], v[2:5]
	v_mfma_f32_16x16x32_bf16 v[6:9], v[130:133], v[186:189], v[6:9]
	v_mfma_f32_16x16x32_bf16 v[54:57], v[138:141], v[166:169], v[54:57]
	v_mfma_f32_16x16x32_bf16 v[50:53], v[154:157], v[166:169], v[50:53]
	v_mfma_f32_16x16x32_bf16 v[34:37], v[154:157], v[174:177], v[34:37]
	v_mfma_f32_16x16x32_bf16 v[38:41], v[138:141], v[174:177], v[38:41]
	v_mfma_f32_16x16x32_bf16 v[22:25], v[138:141], v[182:185], v[22:25]
	v_mfma_f32_16x16x32_bf16 v[18:21], v[154:157], v[182:185], v[18:21]
	v_mfma_f32_16x16x32_bf16 v[2:5], v[154:157], v[190:193], v[2:5]
	v_mfma_f32_16x16x32_bf16 v[6:9], v[138:141], v[190:193], v[6:9]
	s_barrier
	s_add_u32 s6, s6, s98
	s_addc_u32 s7, s7, 0
	s_add_u32 s6, s6, s98
	s_addc_u32 s7, s7, 0
	s_add_u32 s67, s67, s98
	s_addc_u32 s85, s85, 0
	s_add_u32 s67, s67, s98
	s_addc_u32 s85, s85, 0
	s_cmp_ge_u32 vcc_lo, s69
	s_mov_b32 s8, vcc_lo
	s_cbranch_scc0 .LBB0_175
	s_branch .Lpeelx175
.LBB0_175:
	s_add_i32 vcc_lo, s8, 2
	s_add_u32 s4, s6, s98
	s_addc_u32 s5, s7, 0
	s_add_i32 vcc_hi, 0, 0x10000
	s_cmp_eq_u32 s13, s8
	s_cselect_b32 s9, s1, s5
	s_cselect_b32 s8, s0, s4
	s_cselect_b32 s5, s97, s85
	s_cselect_b32 s4, s96, s67
	s_add_i32 s84, 0, 0x14000
	v_add_u32_e32 v122, vcc_hi, v248
	v_add_u32_e32 v154, s84, v248
	ds_read_b128 v[98:101], v122
	ds_read_b128 v[102:105], v122 offset:1024
	ds_read_b128 v[114:117], v122 offset:2048
	ds_read_b128 v[122:125], v122 offset:3072
	ds_read_b128 v[130:133], v154
	ds_read_b128 v[138:141], v154 offset:1024
	ds_read_b128 v[146:149], v154 offset:2048
	ds_read_b128 v[154:157], v154 offset:3072
	v_lshl_add_u64 v[206:207], s[6:7], 0, v[200:201]
	s_add_i32 m0, s81, 0xc000
	ds_read_b128 v[162:165], v249
	ds_read_b128 v[166:169], v249 offset:1024
	ds_read_b128 v[170:173], v249 offset:2048
	ds_read_b128 v[174:177], v249 offset:3072
	ds_read_b128 v[178:181], v249 offset:4096
	ds_read_b128 v[182:185], v249 offset:5120
	ds_read_b128 v[186:189], v249 offset:6144
	ds_read_b128 v[190:193], v249 offset:7168
	global_load_lds_dwordx4 v[206:207], off
	v_lshl_add_u64 v[206:207], s[6:7], 0, v[210:211]
	s_add_i32 m0, s81, 0xe000
	s_nop 0
	global_load_lds_dwordx4 v[206:207], off
	s_waitcnt vmcnt(8)
	s_waitcnt lgkmcnt(0)
	s_barrier
; #define PG8_STAGE(bufoff, gbase, voff) do { _Pragma("unroll") for (int _i = 0; _i < 2; ++_i) \
;         __builtin_amdgcn_global_load_lds((const unsigned*)((const char*)(gbase) + (voff)[_i]), (PG8_LAS unsigned*)(lds + (bufoff) + ldsw + _i * 8192), 16, 0, 0); } while (0)
; #define PG8_LDA(dst, b, h) do { _Pragma("unroll") for (int m = 0; m < 4; ++m) _Pragma("unroll") for (int k = 0; k < 2; ++k) dst[m][k] = *(const PG8_LAS bf16x8*)(lds + PG8_SA(b, h) + aoff + m * 2048 + k * 1024); } while (0)
; #define PG8_MMA(ai, bj, At, Bt) do { __builtin_amdgcn_s_setprio(1); _Pragma("unroll") for (int m = 0; m < 4; ++m) _Pragma("unroll") for (int n = 0; n < 2; ++n) _Pragma("unroll") for (int k = 0; k < 2; ++k) \
;         acc[ai][bj][m][n] = mma16<Epi::I8>(Bt[n][k], At[m][k], acc[ai][bj][m][n]); __builtin_amdgcn_s_setprio(0); } while (0)
; #define PG8_WAIT_V(n) asm volatile("s_waitcnt vmcnt(" #n ")" ::: "memory")
; #define PG8_WAIT_L(n) asm volatile("s_waitcnt lgkmcnt(" #n ")" ::: "memory")
; #define PG8_BAR __builtin_amdgcn_s_barrier()
; #define PG8_SCHED __builtin_amdgcn_sched_barrier(0)
; template <class Epi, class Sched, bool ALIGN_EPI = false, bool SP2 = false>
; __device__ __forceinline__ void gemm_phase(PG8_LAS unsigned char* lds, const Gemm g, const Sched& S, const Epi& E) {
;     ...
;             PG8_WAIT_V(8); PG8_WAIT_L(0); PG8_BAR; PG8_MMA(0, 0, At, B0); PG8_MMA(0, 1, At, B1); PG8_BAR; PG8_SCHED;
;             PG8_LDA(At, 0, 1); PG8_STAGE(PG8_SB(0, 0), b2, voffB); PG8_STAGE(PG8_SB(0, 1), b2 + hstep, voffB); PG8_STAGE(PG8_SA(0, 0), a2, voffA);
;             PG8_WAIT_V(8); PG8_WAIT_L(0); PG8_BAR; PG8_MMA(1, 0, At, B0); PG8_MMA(1, 1, At, B1); PG8_BAR; PG8_SCHED;
	s_waitcnt lgkmcnt(0)
	v_mfma_f32_16x16x32_bf16 v[158:161], v[98:101], v[162:165], v[158:161]
	v_mfma_f32_16x16x32_bf16 v[150:153], v[114:117], v[162:165], v[150:153]
	v_mfma_f32_16x16x32_bf16 v[118:121], v[114:117], v[170:173], v[118:121]
	v_mfma_f32_16x16x32_bf16 v[126:129], v[98:101], v[170:173], v[126:129]
	v_mfma_f32_16x16x32_bf16 v[94:97], v[98:101], v[178:181], v[94:97]
	v_mfma_f32_16x16x32_bf16 v[90:93], v[114:117], v[178:181], v[90:93]
	v_mfma_f32_16x16x32_bf16 v[74:77], v[114:117], v[186:189], v[74:77]
	v_mfma_f32_16x16x32_bf16 v[78:81], v[98:101], v[186:189], v[78:81]
	v_mfma_f32_16x16x32_bf16 v[158:161], v[102:105], v[166:169], v[158:161]
	v_mfma_f32_16x16x32_bf16 v[150:153], v[122:125], v[166:169], v[150:153]
	v_mfma_f32_16x16x32_bf16 v[118:121], v[122:125], v[174:177], v[118:121]
	v_mfma_f32_16x16x32_bf16 v[126:129], v[102:105], v[174:177], v[126:129]
	v_mfma_f32_16x16x32_bf16 v[94:97], v[102:105], v[182:185], v[94:97]
	v_mfma_f32_16x16x32_bf16 v[90:93], v[122:125], v[182:185], v[90:93]
	v_mfma_f32_16x16x32_bf16 v[74:77], v[122:125], v[190:193], v[74:77]
	v_mfma_f32_16x16x32_bf16 v[78:81], v[102:105], v[190:193], v[78:81]
	v_mfma_f32_16x16x32_bf16 v[142:145], v[130:133], v[162:165], v[142:145]
	v_mfma_f32_16x16x32_bf16 v[134:137], v[146:149], v[162:165], v[134:137]
	v_mfma_f32_16x16x32_bf16 v[106:109], v[146:149], v[170:173], v[106:109]
	v_mfma_f32_16x16x32_bf16 v[110:113], v[130:133], v[170:173], v[110:113]
	v_mfma_f32_16x16x32_bf16 v[86:89], v[130:133], v[178:181], v[86:89]
	v_mfma_f32_16x16x32_bf16 v[82:85], v[146:149], v[178:181], v[82:85]
	v_mfma_f32_16x16x32_bf16 v[66:69], v[146:149], v[186:189], v[66:69]
	v_mfma_f32_16x16x32_bf16 v[70:73], v[130:133], v[186:189], v[70:73]
	v_mfma_f32_16x16x32_bf16 v[142:145], v[138:141], v[166:169], v[142:145]
	v_mfma_f32_16x16x32_bf16 v[134:137], v[154:157], v[166:169], v[134:137]
	v_mfma_f32_16x16x32_bf16 v[106:109], v[154:157], v[174:177], v[106:109]
	v_mfma_f32_16x16x32_bf16 v[110:113], v[138:141], v[174:177], v[110:113]
	v_mfma_f32_16x16x32_bf16 v[86:89], v[138:141], v[182:185], v[86:89]
	v_mfma_f32_16x16x32_bf16 v[82:85], v[154:157], v[182:185], v[82:85]
	v_mfma_f32_16x16x32_bf16 v[66:69], v[154:157], v[190:193], v[66:69]
	v_mfma_f32_16x16x32_bf16 v[70:73], v[138:141], v[190:193], v[70:73]
	s_barrier
	s_add_i32 vcc_hi, vcc_hi, s80
	v_lshl_add_u64 v[206:207], s[4:5], 0, v[0:1]
	s_mov_b32 m0, vcc_hi
	ds_read_b128 v[162:165], v249 offset:16384
	ds_read_b128 v[166:169], v249 offset:17408
	ds_read_b128 v[170:173], v249 offset:18432
	ds_read_b128 v[174:177], v249 offset:19456
	ds_read_b128 v[178:181], v249 offset:20480
	ds_read_b128 v[182:185], v249 offset:21504
	ds_read_b128 v[186:189], v249 offset:22528
	ds_read_b128 v[190:193], v249 offset:23552
	global_load_lds_dwordx4 v[206:207], off
	s_add_i32 m0, vcc_hi, 0x2000
	v_lshl_add_u64 v[212:213], s[4:5], 0, v[198:199]
	s_add_u32 s4, s4, s100
	s_addc_u32 s5, s5, 0
	s_add_i32 s84, s84, s80
	global_load_lds_dwordx4 v[212:213], off
	v_lshl_add_u64 v[214:215], s[4:5], 0, v[0:1]
	s_mov_b32 m0, s84
	v_lshl_add_u64 v[216:217], s[4:5], 0, v[198:199]
	global_load_lds_dwordx4 v[214:215], off
	s_add_i32 m0, s84, 0x2000
	v_lshl_add_u64 v[218:219], s[8:9], 0, v[194:195]
	global_load_lds_dwordx4 v[216:217], off
	s_mov_b32 m0, s81
	v_lshl_add_u64 v[220:221], s[8:9], 0, v[196:197]
	global_load_lds_dwordx4 v[218:219], off
	s_mov_b32 m0, s70
	s_nop 0
	global_load_lds_dwordx4 v[220:221], off
	s_waitcnt vmcnt(8)
	s_waitcnt lgkmcnt(0)
	s_barrier
	s_waitcnt lgkmcnt(0)
	v_mfma_f32_16x16x32_bf16 v[62:65], v[98:101], v[162:165], v[62:65]
	v_mfma_f32_16x16x32_bf16 v[58:61], v[114:117], v[162:165], v[58:61]
	v_mfma_f32_16x16x32_bf16 v[42:45], v[114:117], v[170:173], v[42:45]
	v_mfma_f32_16x16x32_bf16 v[46:49], v[98:101], v[170:173], v[46:49]
	v_mfma_f32_16x16x32_bf16 v[30:33], v[98:101], v[178:181], v[30:33]
	v_mfma_f32_16x16x32_bf16 v[26:29], v[114:117], v[178:181], v[26:29]
	v_mfma_f32_16x16x32_bf16 v[10:13], v[114:117], v[186:189], v[10:13]
	v_mfma_f32_16x16x32_bf16 v[14:17], v[98:101], v[186:189], v[14:17]
	v_mfma_f32_16x16x32_bf16 v[62:65], v[102:105], v[166:169], v[62:65]
	v_mfma_f32_16x16x32_bf16 v[58:61], v[122:125], v[166:169], v[58:61]
	v_mfma_f32_16x16x32_bf16 v[42:45], v[122:125], v[174:177], v[42:45]
	v_mfma_f32_16x16x32_bf16 v[46:49], v[102:105], v[174:177], v[46:49]
	v_mfma_f32_16x16x32_bf16 v[30:33], v[102:105], v[182:185], v[30:33]
	v_mfma_f32_16x16x32_bf16 v[26:29], v[122:125], v[182:185], v[26:29]
	v_mfma_f32_16x16x32_bf16 v[10:13], v[122:125], v[190:193], v[10:13]
	v_mfma_f32_16x16x32_bf16 v[14:17], v[102:105], v[190:193], v[14:17]
	v_mfma_f32_16x16x32_bf16 v[54:57], v[130:133], v[162:165], v[54:57]
	v_mfma_f32_16x16x32_bf16 v[50:53], v[146:149], v[162:165], v[50:53]
	v_mfma_f32_16x16x32_bf16 v[34:37], v[146:149], v[170:173], v[34:37]
	v_mfma_f32_16x16x32_bf16 v[38:41], v[130:133], v[170:173], v[38:41]
	v_mfma_f32_16x16x32_bf16 v[22:25], v[130:133], v[178:181], v[22:25]
	v_mfma_f32_16x16x32_bf16 v[18:21], v[146:149], v[178:181], v[18:21]
	v_mfma_f32_16x16x32_bf16 v[2:5], v[146:149], v[186:189], v[2:5]
	v_mfma_f32_16x16x32_bf16 v[6:9], v[130:133], v[186:189], v[6:9]
	v_mfma_f32_16x16x32_bf16 v[54:57], v[138:141], v[166:169], v[54:57]
	v_mfma_f32_16x16x32_bf16 v[50:53], v[154:157], v[166:169], v[50:53]
	v_mfma_f32_16x16x32_bf16 v[34:37], v[154:157], v[174:177], v[34:37]
	v_mfma_f32_16x16x32_bf16 v[38:41], v[138:141], v[174:177], v[38:41]
	v_mfma_f32_16x16x32_bf16 v[22:25], v[138:141], v[182:185], v[22:25]
	v_mfma_f32_16x16x32_bf16 v[18:21], v[154:157], v[182:185], v[18:21]
	v_mfma_f32_16x16x32_bf16 v[2:5], v[154:157], v[190:193], v[2:5]
	v_mfma_f32_16x16x32_bf16 v[6:9], v[138:141], v[190:193], v[6:9]
	s_barrier
; #define PG8_STAGE(bufoff, gbase, voff) do { _Pragma("unroll") for (int _i = 0; _i < 2; ++_i) \
;         __builtin_amdgcn_global_load_lds((const unsigned*)((const char*)(gbase) + (voff)[_i]), (PG8_LAS unsigned*)(lds + (bufoff) + ldsw + _i * 8192), 16, 0, 0); } while (0)
; #define PG8_LDA(dst, b, h) do { _Pragma("unroll") for (int m = 0; m < 4; ++m) _Pragma("unroll") for (int k = 0; k < 2; ++k) dst[m][k] = *(const PG8_LAS bf16x8*)(lds + PG8_SA(b, h) + aoff + m * 2048 + k * 1024); } while (0)
; #define PG8_LDB(dst, b, h) do { _Pragma("unroll") for (int n = 0; n < 2; ++n) _Pragma("unroll") for (int k = 0; k < 2; ++k) dst[n][k] = *(const PG8_LAS bf16x8*)(lds + PG8_SB(b, h) + boff + n * 2048 + k * 1024); } while (0)
; #define PG8_MMA(ai, bj, At, Bt) do { __builtin_amdgcn_s_setprio(1); _Pragma("unroll") for (int m = 0; m < 4; ++m) _Pragma("unroll") for (int n = 0; n < 2; ++n) _Pragma("unroll") for (int k = 0; k < 2; ++k) \
;         acc[ai][bj][m][n] = mma16<Epi::I8>(Bt[n][k], At[m][k], acc[ai][bj][m][n]); __builtin_amdgcn_s_setprio(0); } while (0)
; #define PG8_WAIT_V(n) asm volatile("s_waitcnt vmcnt(" #n ")" ::: "memory")
; #define PG8_WAIT_L(n) asm volatile("s_waitcnt lgkmcnt(" #n ")" ::: "memory")
; #define PG8_BAR __builtin_amdgcn_s_barrier()
; #define PG8_SCHED __builtin_amdgcn_sched_barrier(0)
; template <class Epi, class Sched, bool ALIGN_EPI = false, bool SP2 = false>
; __device__ __forceinline__ void gemm_phase(PG8_LAS unsigned char* lds, const Gemm g, const Sched& S, const Epi& E) {
;     ...
;             PG8_LDB(B0, 1, 0); PG8_LDB(B1, 1, 1); PG8_SCHED; PG8_LDA(At, 1, 0); PG8_STAGE(PG8_SA(0, 1), a2 + hstep, voffA);
;             PG8_WAIT_V(8); PG8_WAIT_L(0); PG8_BAR; PG8_MMA(0, 0, At, B0); PG8_MMA(0, 1, At, B1); PG8_BAR; PG8_SCHED;
	s_add_i32 s84, 0, 0x18000
	s_add_i32 vcc_hi, 0, 0x1c000
	v_add_u32_e32 v122, s84, v248
	v_add_u32_e32 v154, vcc_hi, v248
	ds_read_b128 v[98:101], v122
	ds_read_b128 v[102:105], v122 offset:1024
	ds_read_b128 v[114:117], v122 offset:2048
	ds_read_b128 v[122:125], v122 offset:3072
	ds_read_b128 v[130:133], v154
	ds_read_b128 v[138:141], v154 offset:1024
	ds_read_b128 v[146:149], v154 offset:2048
	ds_read_b128 v[154:157], v154 offset:3072
	s_add_u32 s4, s8, s100
	s_addc_u32 s5, s9, 0
	s_mov_b32 m0, s71
	v_lshl_add_u64 v[222:223], s[4:5], 0, v[194:195]
	ds_read_b128 v[162:165], v249 offset:32768
	ds_read_b128 v[166:169], v249 offset:33792
	ds_read_b128 v[170:173], v249 offset:34816
	ds_read_b128 v[174:177], v249 offset:35840
	ds_read_b128 v[178:181], v249 offset:36864
	ds_read_b128 v[182:185], v249 offset:37888
	ds_read_b128 v[186:189], v249 offset:38912
	ds_read_b128 v[190:193], v249 offset:39936
	global_load_lds_dwordx4 v[222:223], off
	v_lshl_add_u64 v[222:223], s[4:5], 0, v[196:197]
	s_mov_b32 m0, s12
	s_nop 0
	global_load_lds_dwordx4 v[222:223], off
	s_waitcnt vmcnt(8)
	s_waitcnt lgkmcnt(0)
	s_barrier
	s_waitcnt lgkmcnt(0)
	v_mfma_f32_16x16x32_bf16 v[158:161], v[98:101], v[162:165], v[158:161]
	v_mfma_f32_16x16x32_bf16 v[150:153], v[114:117], v[162:165], v[150:153]
	v_mfma_f32_16x16x32_bf16 v[118:121], v[114:117], v[170:173], v[118:121]
	v_mfma_f32_16x16x32_bf16 v[126:129], v[98:101], v[170:173], v[126:129]
	v_mfma_f32_16x16x32_bf16 v[94:97], v[98:101], v[178:181], v[94:97]
	v_mfma_f32_16x16x32_bf16 v[90:93], v[114:117], v[178:181], v[90:93]
	v_mfma_f32_16x16x32_bf16 v[74:77], v[114:117], v[186:189], v[74:77]
	v_mfma_f32_16x16x32_bf16 v[78:81], v[98:101], v[186:189], v[78:81]
	v_mfma_f32_16x16x32_bf16 v[158:161], v[102:105], v[166:169], v[158:161]
	v_mfma_f32_16x16x32_bf16 v[150:153], v[122:125], v[166:169], v[150:153]
	v_mfma_f32_16x16x32_bf16 v[118:121], v[122:125], v[174:177], v[118:121]
	v_mfma_f32_16x16x32_bf16 v[126:129], v[102:105], v[174:177], v[126:129]
	v_mfma_f32_16x16x32_bf16 v[94:97], v[102:105], v[182:185], v[94:97]
	v_mfma_f32_16x16x32_bf16 v[90:93], v[122:125], v[182:185], v[90:93]
	v_mfma_f32_16x16x32_bf16 v[74:77], v[122:125], v[190:193], v[74:77]
	v_mfma_f32_16x16x32_bf16 v[78:81], v[102:105], v[190:193], v[78:81]
	v_mfma_f32_16x16x32_bf16 v[142:145], v[130:133], v[162:165], v[142:145]
	v_mfma_f32_16x16x32_bf16 v[134:137], v[146:149], v[162:165], v[134:137]
	v_mfma_f32_16x16x32_bf16 v[106:109], v[146:149], v[170:173], v[106:109]
	v_mfma_f32_16x16x32_bf16 v[110:113], v[130:133], v[170:173], v[110:113]
	v_mfma_f32_16x16x32_bf16 v[86:89], v[130:133], v[178:181], v[86:89]
	v_mfma_f32_16x16x32_bf16 v[82:85], v[146:149], v[178:181], v[82:85]
	v_mfma_f32_16x16x32_bf16 v[66:69], v[146:149], v[186:189], v[66:69]
	v_mfma_f32_16x16x32_bf16 v[70:73], v[130:133], v[186:189], v[70:73]
	v_mfma_f32_16x16x32_bf16 v[142:145], v[138:141], v[166:169], v[142:145]
	v_mfma_f32_16x16x32_bf16 v[134:137], v[154:157], v[166:169], v[134:137]
	v_mfma_f32_16x16x32_bf16 v[106:109], v[154:157], v[174:177], v[106:109]
	v_mfma_f32_16x16x32_bf16 v[110:113], v[138:141], v[174:177], v[110:113]
	v_mfma_f32_16x16x32_bf16 v[86:89], v[138:141], v[182:185], v[86:89]
	v_mfma_f32_16x16x32_bf16 v[82:85], v[154:157], v[182:185], v[82:85]
	v_mfma_f32_16x16x32_bf16 v[66:69], v[154:157], v[190:193], v[66:69]
	v_mfma_f32_16x16x32_bf16 v[70:73], v[138:141], v[190:193], v[70:73]
	s_barrier
; #define PG8_STAGE(bufoff, gbase, voff) do { _Pragma("unroll") for (int _i = 0; _i < 2; ++_i) \
;         __builtin_amdgcn_global_load_lds((const unsigned*)((const char*)(gbase) + (voff)[_i]), (PG8_LAS unsigned*)(lds + (bufoff) + ldsw + _i * 8192), 16, 0, 0); } while (0)
; #define PG8_LDA(dst, b, h) do { _Pragma("unroll") for (int m = 0; m < 4; ++m) _Pragma("unroll") for (int k = 0; k < 2; ++k) dst[m][k] = *(const PG8_LAS bf16x8*)(lds + PG8_SA(b, h) + aoff + m * 2048 + k * 1024); } while (0)
; #define PG8_MMA(ai, bj, At, Bt) do { __builtin_amdgcn_s_setprio(1); _Pragma("unroll") for (int m = 0; m < 4; ++m) _Pragma("unroll") for (int n = 0; n < 2; ++n) _Pragma("unroll") for (int k = 0; k < 2; ++k) \
;         acc[ai][bj][m][n] = mma16<Epi::I8>(Bt[n][k], At[m][k], acc[ai][bj][m][n]); __builtin_amdgcn_s_setprio(0); } while (0)
; #define PG8_WAIT_V(n) asm volatile("s_waitcnt vmcnt(" #n ")" ::: "memory")
; #define PG8_WAIT_L(n) asm volatile("s_waitcnt lgkmcnt(" #n ")" ::: "memory")
; #define PG8_BAR __builtin_amdgcn_s_barrier()
; #define PG8_SCHED __builtin_amdgcn_sched_barrier(0)
; template <class Epi, class Sched, bool ALIGN_EPI = false, bool SP2 = false>
; __device__ __forceinline__ void gemm_phase(PG8_LAS unsigned char* lds, const Gemm g, const Sched& S, const Epi& E) {
;     ...
;         for (int t = 0; t < nt; t += 2) {
;             const bool last = (t == nt - 2);
;             const char* a1 = cA + (size_t)(t + 1) * kstep;
;             const char* a2 = last ? nA : cA + (size_t)(t + 2) * kstep; const char* b2 = last ? nB : cB + (size_t)(t + 2) * kstep;
;     ...
;             PG8_LDA(At, 1, 1); PG8_STAGE(PG8_SB(1, 0), b3, voffB); PG8_STAGE(PG8_SB(1, 1), b3 + hstep, voffB); PG8_STAGE(PG8_SA(1, 0), a3, voffA);
;             PG8_WAIT_V(8); PG8_WAIT_L(0); PG8_BAR; PG8_MMA(1, 0, At, B0); PG8_MMA(1, 1, At, B1); PG8_BAR; PG8_SCHED;
	s_add_i32 s4, s84, s80
	v_lshl_add_u64 v[206:207], v[206:207], 0, s[98:99]
	s_mov_b32 m0, s4
	ds_read_b128 v[162:165], v249 offset:49152
	ds_read_b128 v[166:169], v249 offset:50176
	ds_read_b128 v[170:173], v249 offset:51200
	ds_read_b128 v[174:177], v249 offset:52224
	ds_read_b128 v[178:181], v249 offset:53248
	ds_read_b128 v[182:185], v249 offset:54272
	ds_read_b128 v[186:189], v249 offset:55296
	ds_read_b128 v[190:193], v249 offset:56320
	global_load_lds_dwordx4 v[206:207], off
	v_lshl_add_u64 v[206:207], v[212:213], 0, s[98:99]
	s_add_i32 m0, s4, 0x2000
	s_add_i32 s4, vcc_hi, s80
	global_load_lds_dwordx4 v[206:207], off
	v_lshl_add_u64 v[206:207], v[214:215], 0, s[98:99]
	s_mov_b32 m0, s4
	s_nop 0
	global_load_lds_dwordx4 v[206:207], off
	v_lshl_add_u64 v[206:207], v[216:217], 0, s[98:99]
	s_add_i32 m0, s4, 0x2000
	s_nop 0
	global_load_lds_dwordx4 v[206:207], off
	v_lshl_add_u64 v[206:207], v[218:219], 0, s[98:99]
	s_mov_b32 m0, s10
	s_nop 0
	global_load_lds_dwordx4 v[206:207], off
	v_lshl_add_u64 v[206:207], v[220:221], 0, s[98:99]
	s_mov_b32 m0, s11
	s_nop 0
	global_load_lds_dwordx4 v[206:207], off
	s_waitcnt vmcnt(8)
	s_waitcnt lgkmcnt(0)
	s_barrier
	s_waitcnt lgkmcnt(0)
	v_mfma_f32_16x16x32_bf16 v[62:65], v[98:101], v[162:165], v[62:65]
	v_mfma_f32_16x16x32_bf16 v[58:61], v[114:117], v[162:165], v[58:61]
	v_mfma_f32_16x16x32_bf16 v[42:45], v[114:117], v[170:173], v[42:45]
	v_mfma_f32_16x16x32_bf16 v[46:49], v[98:101], v[170:173], v[46:49]
	v_mfma_f32_16x16x32_bf16 v[30:33], v[98:101], v[178:181], v[30:33]
	v_mfma_f32_16x16x32_bf16 v[26:29], v[114:117], v[178:181], v[26:29]
	v_mfma_f32_16x16x32_bf16 v[10:13], v[114:117], v[186:189], v[10:13]
	v_mfma_f32_16x16x32_bf16 v[14:17], v[98:101], v[186:189], v[14:17]
	v_mfma_f32_16x16x32_bf16 v[62:65], v[102:105], v[166:169], v[62:65]
	v_mfma_f32_16x16x32_bf16 v[58:61], v[122:125], v[166:169], v[58:61]
	v_mfma_f32_16x16x32_bf16 v[42:45], v[122:125], v[174:177], v[42:45]
	v_mfma_f32_16x16x32_bf16 v[46:49], v[102:105], v[174:177], v[46:49]
	v_mfma_f32_16x16x32_bf16 v[30:33], v[102:105], v[182:185], v[30:33]
	v_mfma_f32_16x16x32_bf16 v[26:29], v[122:125], v[182:185], v[26:29]
	v_mfma_f32_16x16x32_bf16 v[10:13], v[122:125], v[190:193], v[10:13]
	v_mfma_f32_16x16x32_bf16 v[14:17], v[102:105], v[190:193], v[14:17]
	v_mfma_f32_16x16x32_bf16 v[54:57], v[130:133], v[162:165], v[54:57]
	v_mfma_f32_16x16x32_bf16 v[50:53], v[146:149], v[162:165], v[50:53]
	v_mfma_f32_16x16x32_bf16 v[34:37], v[146:149], v[170:173], v[34:37]
	v_mfma_f32_16x16x32_bf16 v[38:41], v[130:133], v[170:173], v[38:41]
	v_mfma_f32_16x16x32_bf16 v[22:25], v[130:133], v[178:181], v[22:25]
	v_mfma_f32_16x16x32_bf16 v[18:21], v[146:149], v[178:181], v[18:21]
	v_mfma_f32_16x16x32_bf16 v[2:5], v[146:149], v[186:189], v[2:5]
	v_mfma_f32_16x16x32_bf16 v[6:9], v[130:133], v[186:189], v[6:9]
	v_mfma_f32_16x16x32_bf16 v[54:57], v[138:141], v[166:169], v[54:57]
	v_mfma_f32_16x16x32_bf16 v[50:53], v[154:157], v[166:169], v[50:53]
	v_mfma_f32_16x16x32_bf16 v[34:37], v[154:157], v[174:177], v[34:37]
	v_mfma_f32_16x16x32_bf16 v[38:41], v[138:141], v[174:177], v[38:41]
	v_mfma_f32_16x16x32_bf16 v[22:25], v[138:141], v[182:185], v[22:25]
	v_mfma_f32_16x16x32_bf16 v[18:21], v[154:157], v[182:185], v[18:21]
	v_mfma_f32_16x16x32_bf16 v[2:5], v[154:157], v[190:193], v[2:5]
	v_mfma_f32_16x16x32_bf16 v[6:9], v[138:141], v[190:193], v[6:9]
	s_barrier
	s_add_u32 s6, s6, s98
	s_addc_u32 s7, s7, 0
	s_add_u32 s6, s6, s98
	s_addc_u32 s7, s7, 0
	s_add_u32 s67, s67, s98
	s_addc_u32 s85, s85, 0
	s_add_u32 s67, s67, s98
	s_addc_u32 s85, s85, 0
	s_cmp_ge_u32 vcc_lo, s69
	s_mov_b32 s8, vcc_lo
	s_cbranch_scc0 .LBB0_175
